# P1: waves 4-7 run the weight transposes before their row norms, waves 0-3 the other way round, so the latency-bound and bandwidth-bound halves overlap
# baseline (speedup 1.0000x reference)
.LBB0_82:
	s_load_dwordx16 s[80:95], s[0:1], 0x40
	s_load_dwordx16 s[4:19], s[0:1], 0x80
	v_writelane_b32 v244, s50, 7
	s_cmp_lt_i32 s56, 2
	s_cselect_b64 s[0:1], -1, 0
	v_writelane_b32 v244, s51, 8
	s_waitcnt lgkmcnt(0)
	v_writelane_b32 v244, s4, 9
	s_and_b64 s[2:3], s[0:1], s[2:3]
	s_andn2_b64 vcc, exec, s[2:3]
	v_writelane_b32 v244, s5, 10
	v_writelane_b32 v244, s6, 11
	v_writelane_b32 v244, s7, 12
	v_writelane_b32 v244, s8, 13
	v_writelane_b32 v244, s9, 14
	v_writelane_b32 v244, s10, 15
	v_writelane_b32 v244, s11, 16
	v_writelane_b32 v244, s12, 17
	v_writelane_b32 v244, s13, 18
	v_writelane_b32 v244, s14, 19
	v_writelane_b32 v244, s15, 20
	v_writelane_b32 v244, s16, 21
	v_writelane_b32 v244, s17, 22
	v_writelane_b32 v244, s18, 23
	v_writelane_b32 v244, s19, 24
	s_lshl_b32 s4, s33, 3
	v_writelane_b32 v244, s58, 25
	s_add_i32 s58, s58, s4
	s_lshl_b32 s75, s72, 3
	s_cbranch_vccnz .LBB0_183
	v_readlane_b32 s99, v244, 25
	s_mov_b32 s98, 0
	s_cmp_gt_u32 s99, 3
	s_cbranch_scc1 .LBB0_93
.Lp1_A:
	s_cmp_gt_i32 s58, 0x87ff
	s_cbranch_scc1 .Lp1_A_done
	v_mov_b32_e32 v1, 0
	v_lshlrev_b32_e32 v0, 3, v144
	v_lshl_add_u64 v[2:3], s[54:55], 0, v[0:1]
	v_lshlrev_b32_e32 v0, 4, v144
	v_lshl_add_u64 v[22:23], s[76:77], 0, v[0:1]
	v_mbcnt_lo_u32_b32 v1, -1, 0
	s_mov_b64 s[0:1], 0x2400000
	v_mbcnt_hi_u32_b32 v1, -1, v1
	v_lshl_add_u64 v[20:21], v[2:3], 0, s[0:1]
	v_and_b32_e32 v3, 64, v1
	v_add_u32_e32 v3, 64, v3
	v_xor_b32_e32 v5, 1, v1
	v_cmp_lt_i32_e32 vcc, v5, v3
	v_or_b32_e32 v0, 64, v144
	v_or_b32_e32 v2, 0x80, v144
	v_cndmask_b32_e32 v5, v1, v5, vcc
	v_lshlrev_b32_e32 v24, 2, v5
	v_xor_b32_e32 v5, 2, v1
	v_cmp_lt_i32_e32 vcc, v5, v3
	v_or_b32_e32 v4, 0xc0, v144
	s_mov_b32 s1, 0
	v_cndmask_b32_e32 v5, v1, v5, vcc
	v_lshlrev_b32_e32 v25, 2, v5
	v_xor_b32_e32 v5, 4, v1
	v_cmp_lt_i32_e32 vcc, v5, v3
	v_lshlrev_b32_e32 v30, 4, v144
	v_mov_b32_e32 v31, 0x358637bd
	v_cndmask_b32_e32 v5, v1, v5, vcc
	v_lshlrev_b32_e32 v26, 2, v5
	v_xor_b32_e32 v5, 8, v1
	v_cmp_lt_i32_e32 vcc, v5, v3
	v_lshlrev_b32_e32 v32, 4, v0
	v_lshlrev_b32_e32 v33, 4, v2
	v_cndmask_b32_e32 v5, v1, v5, vcc
	v_lshlrev_b32_e32 v27, 2, v5
	v_xor_b32_e32 v5, 16, v1
	v_cmp_lt_i32_e32 vcc, v5, v3
	v_lshlrev_b32_e32 v34, 4, v4
	s_mov_b32 s8, s58
	v_cndmask_b32_e32 v5, v1, v5, vcc
	v_lshlrev_b32_e32 v28, 2, v5
	v_xor_b32_e32 v5, 32, v1
	v_cmp_lt_i32_e32 vcc, v5, v3
	s_nop 1
	v_cndmask_b32_e32 v1, v1, v5, vcc
	v_lshlrev_b32_e32 v29, 2, v1
	s_branch .LBB0_86

.Lp1_A_done:
	s_add_i32 s98, s98, 1
	s_cmp_eq_u32 s98, 2
	s_cbranch_scc1 .LBB0_176

.Lp1_B_done:
	s_add_i32 s98, s98, 1
	s_cmp_eq_u32 s98, 2
	s_cbranch_scc0 .Lp1_A
